# nt (non-temporal) hint on the f32 new_k/new_v output stores of the QKV epilogue (never re-read by the kernel)
# speedup vs baseline: 1.0112x; 1.0027x over previous
.LBB0_356:
	s_lshl_b64 s[78:79], s[78:79], 9
	s_add_u32 s76, s76, s78
	s_addc_u32 s77, s77, s79
	s_and_b64 s[74:75], s[74:75], exec
	s_cselect_b32 s30, 0x1000000, 0
	s_add_u32 s30, s4, s30
	s_addc_u32 s31, s5, 0
	s_lshl_b32 s4, s70, 1
	s_or_b32 s4, s4, s83
	s_ashr_i32 s5, s4, 31
	s_lshl_b64 s[4:5], s[4:5], 18
	s_add_u32 s4, s30, s4
	s_addc_u32 s5, s31, s5
	v_lshl_add_u64 v[158:159], v[154:155], 2, s[4:5]
	s_mov_b64 s[4:5], 0x4000000
	v_lshl_add_u64 v[156:157], v[154:155], 1, s[76:77]
	v_lshl_add_u64 v[158:159], v[158:159], 0, s[4:5]
	s_andn2_b64 vcc, exec, s[72:73]
	s_mov_b64 s[4:5], -1
	s_cbranch_vccnz .LBB0_362
	s_and_b64 vcc, exec, s[66:67]
	s_cbranch_vccz .LBB0_359
	s_add_i32 s4, 0, 0x20000
	v_lshlrev_b32_e32 v160, 8, v182
	v_lshl_add_u32 v176, v182, 5, s4
	v_ashrrev_i32_e32 v161, 31, v160
	v_lshl_add_u64 v[168:169], v[160:161], 1, v[156:157]
	v_lshl_add_u64 v[170:171], v[160:161], 2, v[158:159]
	ds_read_b128 v[160:163], v176
	s_waitcnt lgkmcnt(0)
	v_mov_b32_e32 v164, v161
	v_mov_b32_e32 v165, v162
	v_mov_b32_e32 v161, v163
	v_pk_add_f32 v[160:161], v[164:165], v[160:161]
	s_nop 0
	v_add_f32_e32 v96, v160, v161
	v_fmamk_f32 v96, v96, 0x3c000000, v251
	v_rsq_f32_e32 v96, v96
	s_nop 0
	v_pk_mul_f32 v[160:161], v[126:127], v[96:97] op_sel_hi:[1,0]
	v_pk_mul_f32 v[162:163], v[128:129], v[96:97] op_sel_hi:[1,0]
	s_waitcnt vmcnt(0)
	v_pk_mul_f32 v[160:161], v[134:135], v[160:161]
	v_pk_mul_f32 v[162:163], v[136:137], v[162:163]
	v_pk_mul_f32 v[164:165], v[122:123], v[96:97] op_sel_hi:[1,0]
	v_pk_mul_f32 v[166:167], v[124:125], v[96:97] op_sel_hi:[1,0]
	v_cvt_pk_bf16_f32 v172, v160, v161
	v_cvt_pk_bf16_f32 v173, v162, v163
	v_pk_mul_f32 v[164:165], v[130:131], v[164:165]
	v_pk_mul_f32 v[166:167], v[132:133], v[166:167]
	v_cvt_pk_bf16_f32 v174, v164, v165
	s_nop 0
	v_cvt_pk_bf16_f32 v175, v166, v167
	global_store_dwordx2 v[168:169], v[172:173], off
	global_store_dwordx2 v[168:169], v[174:175], off offset:64
	global_store_dwordx4 v[170:171], v[160:163], off nt
	global_store_dwordx4 v[170:171], v[164:167], off offset:128 nt
	ds_read_b128 v[160:163], v176 offset:16
	s_waitcnt lgkmcnt(0)
	v_mov_b32_e32 v164, v161
	v_mov_b32_e32 v165, v162
	v_mov_b32_e32 v161, v163
	v_pk_add_f32 v[160:161], v[164:165], v[160:161]
	s_nop 0
	v_add_f32_e32 v96, v160, v161
	v_fmamk_f32 v96, v96, 0x3c000000, v251
	v_rsq_f32_e32 v96, v96
	s_nop 0
	v_pk_mul_f32 v[160:161], v[118:119], v[96:97] op_sel_hi:[1,0]
	v_pk_mul_f32 v[162:163], v[120:121], v[96:97] op_sel_hi:[1,0]
	v_pk_mul_f32 v[160:161], v[134:135], v[160:161]
	v_pk_mul_f32 v[162:163], v[136:137], v[162:163]
	v_pk_mul_f32 v[164:165], v[114:115], v[96:97] op_sel_hi:[1,0]
	v_pk_mul_f32 v[166:167], v[116:117], v[96:97] op_sel_hi:[1,0]
	v_cvt_pk_bf16_f32 v172, v160, v161
	v_cvt_pk_bf16_f32 v173, v162, v163
	v_pk_mul_f32 v[164:165], v[130:131], v[164:165]
	v_pk_mul_f32 v[166:167], v[132:133], v[166:167]
	v_cvt_pk_bf16_f32 v174, v164, v165
	s_nop 0
	v_cvt_pk_bf16_f32 v175, v166, v167
	global_store_dwordx2 v[168:169], v[172:173], off offset:256
	global_store_dwordx2 v[168:169], v[174:175], off offset:320
	global_store_dwordx4 v[170:171], v[160:163], off offset:512 nt
	global_store_dwordx4 v[170:171], v[164:167], off offset:640 nt
	v_add_u32_e32 v96, 16, v182
	v_lshlrev_b32_e32 v160, 8, v96
	v_lshl_add_u32 v176, v96, 5, s4
	v_ashrrev_i32_e32 v161, 31, v160
	v_lshl_add_u64 v[168:169], v[160:161], 1, v[156:157]
	v_lshl_add_u64 v[170:171], v[160:161], 2, v[158:159]
	ds_read_b128 v[160:163], v176
	s_waitcnt lgkmcnt(0)
	v_mov_b32_e32 v164, v161
	v_mov_b32_e32 v165, v162
	v_mov_b32_e32 v161, v163
	v_pk_add_f32 v[160:161], v[164:165], v[160:161]
	s_nop 0
	v_add_f32_e32 v96, v160, v161
	v_fmamk_f32 v96, v96, 0x3c000000, v251
	v_rsq_f32_e32 v96, v96
	s_nop 0
	v_pk_mul_f32 v[160:161], v[110:111], v[96:97] op_sel_hi:[1,0]
	v_pk_mul_f32 v[162:163], v[112:113], v[96:97] op_sel_hi:[1,0]
	v_pk_mul_f32 v[160:161], v[134:135], v[160:161]
	v_pk_mul_f32 v[162:163], v[136:137], v[162:163]
	v_pk_mul_f32 v[164:165], v[106:107], v[96:97] op_sel_hi:[1,0]
	v_pk_mul_f32 v[166:167], v[108:109], v[96:97] op_sel_hi:[1,0]
	v_cvt_pk_bf16_f32 v172, v160, v161
	v_cvt_pk_bf16_f32 v173, v162, v163
	v_pk_mul_f32 v[164:165], v[130:131], v[164:165]
	v_pk_mul_f32 v[166:167], v[132:133], v[166:167]
	v_cvt_pk_bf16_f32 v174, v164, v165
	s_nop 0
	v_cvt_pk_bf16_f32 v175, v166, v167
	global_store_dwordx2 v[168:169], v[172:173], off
	global_store_dwordx2 v[168:169], v[174:175], off offset:64
	global_store_dwordx4 v[170:171], v[160:163], off nt
	global_store_dwordx4 v[170:171], v[164:167], off offset:128 nt
	ds_read_b128 v[160:163], v176 offset:16
	s_waitcnt lgkmcnt(0)
	v_mov_b32_e32 v164, v161
	v_mov_b32_e32 v165, v162
	v_mov_b32_e32 v161, v163
	v_pk_add_f32 v[160:161], v[164:165], v[160:161]
	s_nop 0
	v_add_f32_e32 v96, v160, v161
	v_fmamk_f32 v96, v96, 0x3c000000, v251
	v_rsq_f32_e32 v96, v96
	s_nop 0
	v_pk_mul_f32 v[160:161], v[102:103], v[96:97] op_sel_hi:[1,0]
	v_pk_mul_f32 v[162:163], v[104:105], v[96:97] op_sel_hi:[1,0]
	v_pk_mul_f32 v[160:161], v[134:135], v[160:161]
	v_pk_mul_f32 v[162:163], v[136:137], v[162:163]
	v_pk_mul_f32 v[164:165], v[98:99], v[96:97] op_sel_hi:[1,0]
	v_pk_mul_f32 v[166:167], v[100:101], v[96:97] op_sel_hi:[1,0]
	v_cvt_pk_bf16_f32 v172, v160, v161
	v_cvt_pk_bf16_f32 v173, v162, v163
	v_pk_mul_f32 v[164:165], v[130:131], v[164:165]
	v_pk_mul_f32 v[166:167], v[132:133], v[166:167]
	v_cvt_pk_bf16_f32 v174, v164, v165
	s_nop 0
	v_cvt_pk_bf16_f32 v175, v166, v167
	global_store_dwordx2 v[168:169], v[172:173], off offset:256
	global_store_dwordx2 v[168:169], v[174:175], off offset:320
	global_store_dwordx4 v[170:171], v[160:163], off offset:512 nt
	global_store_dwordx4 v[170:171], v[164:167], off offset:640 nt
	v_add_u32_e32 v96, 32, v182
	v_lshlrev_b32_e32 v160, 8, v96
	v_lshl_add_u32 v176, v96, 5, s4
	v_ashrrev_i32_e32 v161, 31, v160
	v_lshl_add_u64 v[168:169], v[160:161], 1, v[156:157]
	v_lshl_add_u64 v[170:171], v[160:161], 2, v[158:159]
	ds_read_b128 v[160:163], v176
	s_waitcnt lgkmcnt(0)
	v_mov_b32_e32 v164, v161
	v_mov_b32_e32 v165, v162
	v_mov_b32_e32 v161, v163
	v_pk_add_f32 v[160:161], v[164:165], v[160:161]
	s_nop 0
	v_add_f32_e32 v96, v160, v161
	v_fmamk_f32 v96, v96, 0x3c000000, v251
	v_rsq_f32_e32 v96, v96
	s_nop 0
	v_pk_mul_f32 v[160:161], v[92:93], v[96:97] op_sel_hi:[1,0]
	v_pk_mul_f32 v[162:163], v[94:95], v[96:97] op_sel_hi:[1,0]
	v_pk_mul_f32 v[160:161], v[134:135], v[160:161]
	v_pk_mul_f32 v[162:163], v[136:137], v[162:163]
	v_pk_mul_f32 v[164:165], v[88:89], v[96:97] op_sel_hi:[1,0]
	v_pk_mul_f32 v[166:167], v[90:91], v[96:97] op_sel_hi:[1,0]
	v_cvt_pk_bf16_f32 v172, v160, v161
	v_cvt_pk_bf16_f32 v173, v162, v163
	v_pk_mul_f32 v[164:165], v[130:131], v[164:165]
	v_pk_mul_f32 v[166:167], v[132:133], v[166:167]
	v_cvt_pk_bf16_f32 v174, v164, v165
	s_nop 0
	v_cvt_pk_bf16_f32 v175, v166, v167
	global_store_dwordx2 v[168:169], v[172:173], off
	global_store_dwordx2 v[168:169], v[174:175], off offset:64
	global_store_dwordx4 v[170:171], v[160:163], off nt
	global_store_dwordx4 v[170:171], v[164:167], off offset:128 nt
	ds_read_b128 v[160:163], v176 offset:16
	s_waitcnt lgkmcnt(0)
	v_mov_b32_e32 v164, v161
	v_mov_b32_e32 v165, v162
	v_mov_b32_e32 v161, v163
	v_pk_add_f32 v[160:161], v[164:165], v[160:161]
	s_nop 0
	v_add_f32_e32 v96, v160, v161
	v_fmamk_f32 v96, v96, 0x3c000000, v251
	v_rsq_f32_e32 v96, v96
	s_nop 0
	v_pk_mul_f32 v[160:161], v[84:85], v[96:97] op_sel_hi:[1,0]
	v_pk_mul_f32 v[162:163], v[86:87], v[96:97] op_sel_hi:[1,0]
	v_pk_mul_f32 v[160:161], v[134:135], v[160:161]
	v_pk_mul_f32 v[162:163], v[136:137], v[162:163]
	v_pk_mul_f32 v[164:165], v[80:81], v[96:97] op_sel_hi:[1,0]
	v_pk_mul_f32 v[166:167], v[82:83], v[96:97] op_sel_hi:[1,0]
	v_cvt_pk_bf16_f32 v172, v160, v161
	v_cvt_pk_bf16_f32 v173, v162, v163
	v_pk_mul_f32 v[164:165], v[130:131], v[164:165]
	v_pk_mul_f32 v[166:167], v[132:133], v[166:167]
	v_cvt_pk_bf16_f32 v174, v164, v165
	s_nop 0
	v_cvt_pk_bf16_f32 v175, v166, v167
	global_store_dwordx2 v[168:169], v[172:173], off offset:256
	global_store_dwordx2 v[168:169], v[174:175], off offset:320
	global_store_dwordx4 v[170:171], v[160:163], off offset:512 nt
	global_store_dwordx4 v[170:171], v[164:167], off offset:640 nt
	v_add_u32_e32 v96, 48, v182
	v_lshlrev_b32_e32 v160, 8, v96
	v_lshl_add_u32 v176, v96, 5, s4
	v_ashrrev_i32_e32 v161, 31, v160
	v_lshl_add_u64 v[168:169], v[160:161], 1, v[156:157]
	v_lshl_add_u64 v[170:171], v[160:161], 2, v[158:159]
	ds_read_b128 v[160:163], v176
	s_waitcnt lgkmcnt(0)
	v_mov_b32_e32 v164, v161
	v_mov_b32_e32 v165, v162
	v_mov_b32_e32 v161, v163
	v_pk_add_f32 v[160:161], v[164:165], v[160:161]
	s_nop 0
	v_add_f32_e32 v96, v160, v161
	v_fmamk_f32 v96, v96, 0x3c000000, v251
	v_rsq_f32_e32 v96, v96
	s_nop 0
	v_pk_mul_f32 v[160:161], v[76:77], v[96:97] op_sel_hi:[1,0]
	v_pk_mul_f32 v[162:163], v[78:79], v[96:97] op_sel_hi:[1,0]
	v_pk_mul_f32 v[160:161], v[134:135], v[160:161]
	v_pk_mul_f32 v[162:163], v[136:137], v[162:163]
	v_pk_mul_f32 v[164:165], v[72:73], v[96:97] op_sel_hi:[1,0]
	v_pk_mul_f32 v[166:167], v[74:75], v[96:97] op_sel_hi:[1,0]
	v_cvt_pk_bf16_f32 v172, v160, v161
	v_cvt_pk_bf16_f32 v173, v162, v163
	v_pk_mul_f32 v[164:165], v[130:131], v[164:165]
	v_pk_mul_f32 v[166:167], v[132:133], v[166:167]
	v_cvt_pk_bf16_f32 v174, v164, v165
	s_nop 0
	v_cvt_pk_bf16_f32 v175, v166, v167
	global_store_dwordx2 v[168:169], v[172:173], off
	global_store_dwordx2 v[168:169], v[174:175], off offset:64
	global_store_dwordx4 v[170:171], v[160:163], off nt
	global_store_dwordx4 v[170:171], v[164:167], off offset:128 nt
	ds_read_b128 v[160:163], v176 offset:16
	s_waitcnt lgkmcnt(0)
	v_mov_b32_e32 v164, v161
	v_mov_b32_e32 v165, v162
	v_mov_b32_e32 v161, v163
	v_pk_add_f32 v[160:161], v[164:165], v[160:161]
	s_nop 0
	v_add_f32_e32 v96, v160, v161
	v_fmamk_f32 v96, v96, 0x3c000000, v251
	v_rsq_f32_e32 v96, v96
	s_nop 0
	v_pk_mul_f32 v[160:161], v[68:69], v[96:97] op_sel_hi:[1,0]
	v_pk_mul_f32 v[162:163], v[70:71], v[96:97] op_sel_hi:[1,0]
	v_pk_mul_f32 v[160:161], v[134:135], v[160:161]
	v_pk_mul_f32 v[162:163], v[136:137], v[162:163]
	v_pk_mul_f32 v[164:165], v[64:65], v[96:97] op_sel_hi:[1,0]
	v_pk_mul_f32 v[166:167], v[66:67], v[96:97] op_sel_hi:[1,0]
	v_cvt_pk_bf16_f32 v172, v160, v161
	v_cvt_pk_bf16_f32 v173, v162, v163
	v_pk_mul_f32 v[164:165], v[130:131], v[164:165]
	v_pk_mul_f32 v[166:167], v[132:133], v[166:167]
	v_cvt_pk_bf16_f32 v174, v164, v165
	s_nop 0
	v_cvt_pk_bf16_f32 v175, v166, v167
	global_store_dwordx2 v[168:169], v[172:173], off offset:256
	global_store_dwordx2 v[168:169], v[174:175], off offset:320
	global_store_dwordx4 v[170:171], v[160:163], off offset:512 nt
	global_store_dwordx4 v[170:171], v[164:167], off offset:640 nt
	v_add_u32_e32 v96, 0x80, v182
	v_lshlrev_b32_e32 v160, 8, v96
	v_lshl_add_u32 v176, v96, 5, s4
	v_ashrrev_i32_e32 v161, 31, v160
	v_lshl_add_u64 v[168:169], v[160:161], 1, v[156:157]
	v_lshl_add_u64 v[170:171], v[160:161], 2, v[158:159]
	ds_read_b128 v[160:163], v176
	s_waitcnt lgkmcnt(0)
	v_mov_b32_e32 v164, v161
	v_mov_b32_e32 v165, v162
	v_mov_b32_e32 v161, v163
	v_pk_add_f32 v[160:161], v[164:165], v[160:161]
	s_nop 0
	v_add_f32_e32 v96, v160, v161
	v_fmamk_f32 v96, v96, 0x3c000000, v251
	v_rsq_f32_e32 v96, v96
	s_nop 0
	v_pk_mul_f32 v[160:161], v[60:61], v[96:97] op_sel_hi:[1,0]
	v_pk_mul_f32 v[162:163], v[62:63], v[96:97] op_sel_hi:[1,0]
	v_pk_mul_f32 v[160:161], v[134:135], v[160:161]
	v_pk_mul_f32 v[162:163], v[136:137], v[162:163]
	v_pk_mul_f32 v[164:165], v[56:57], v[96:97] op_sel_hi:[1,0]
	v_pk_mul_f32 v[166:167], v[58:59], v[96:97] op_sel_hi:[1,0]
	v_cvt_pk_bf16_f32 v172, v160, v161
	v_cvt_pk_bf16_f32 v173, v162, v163
	v_pk_mul_f32 v[164:165], v[130:131], v[164:165]
	v_pk_mul_f32 v[166:167], v[132:133], v[166:167]
	v_cvt_pk_bf16_f32 v174, v164, v165
	s_nop 0
	v_cvt_pk_bf16_f32 v175, v166, v167
	global_store_dwordx2 v[168:169], v[172:173], off
	global_store_dwordx2 v[168:169], v[174:175], off offset:64
	global_store_dwordx4 v[170:171], v[160:163], off nt
	global_store_dwordx4 v[170:171], v[164:167], off offset:128 nt
	ds_read_b128 v[160:163], v176 offset:16
	s_waitcnt lgkmcnt(0)
	v_mov_b32_e32 v164, v161
	v_mov_b32_e32 v165, v162
	v_mov_b32_e32 v161, v163
	v_pk_add_f32 v[160:161], v[164:165], v[160:161]
	s_nop 0
	v_add_f32_e32 v96, v160, v161
	v_fmamk_f32 v96, v96, 0x3c000000, v251
	v_rsq_f32_e32 v96, v96
	s_nop 0
	v_pk_mul_f32 v[160:161], v[52:53], v[96:97] op_sel_hi:[1,0]
	v_pk_mul_f32 v[162:163], v[54:55], v[96:97] op_sel_hi:[1,0]
	v_pk_mul_f32 v[160:161], v[134:135], v[160:161]
	v_pk_mul_f32 v[162:163], v[136:137], v[162:163]
	v_pk_mul_f32 v[164:165], v[48:49], v[96:97] op_sel_hi:[1,0]
	v_pk_mul_f32 v[166:167], v[50:51], v[96:97] op_sel_hi:[1,0]
	v_cvt_pk_bf16_f32 v172, v160, v161
	v_cvt_pk_bf16_f32 v173, v162, v163
	v_pk_mul_f32 v[164:165], v[130:131], v[164:165]
	v_pk_mul_f32 v[166:167], v[132:133], v[166:167]
	v_cvt_pk_bf16_f32 v174, v164, v165
	s_nop 0
	v_cvt_pk_bf16_f32 v175, v166, v167
	global_store_dwordx2 v[168:169], v[172:173], off offset:256
	global_store_dwordx2 v[168:169], v[174:175], off offset:320
	global_store_dwordx4 v[170:171], v[160:163], off offset:512 nt
	global_store_dwordx4 v[170:171], v[164:167], off offset:640 nt
	v_add_u32_e32 v96, 0x90, v182
	v_lshlrev_b32_e32 v160, 8, v96
	v_lshl_add_u32 v176, v96, 5, s4
	v_ashrrev_i32_e32 v161, 31, v160
	v_lshl_add_u64 v[168:169], v[160:161], 1, v[156:157]
	v_lshl_add_u64 v[170:171], v[160:161], 2, v[158:159]
	ds_read_b128 v[160:163], v176
	s_waitcnt lgkmcnt(0)
	v_mov_b32_e32 v164, v161
	v_mov_b32_e32 v165, v162
	v_mov_b32_e32 v161, v163
	v_pk_add_f32 v[160:161], v[164:165], v[160:161]
	s_nop 0
	v_add_f32_e32 v96, v160, v161
	v_fmamk_f32 v96, v96, 0x3c000000, v251
	v_rsq_f32_e32 v96, v96
	s_nop 0
	v_pk_mul_f32 v[160:161], v[44:45], v[96:97] op_sel_hi:[1,0]
	v_pk_mul_f32 v[162:163], v[46:47], v[96:97] op_sel_hi:[1,0]
	v_pk_mul_f32 v[160:161], v[134:135], v[160:161]
	v_pk_mul_f32 v[162:163], v[136:137], v[162:163]
	v_pk_mul_f32 v[164:165], v[40:41], v[96:97] op_sel_hi:[1,0]
	v_pk_mul_f32 v[166:167], v[42:43], v[96:97] op_sel_hi:[1,0]
	v_cvt_pk_bf16_f32 v172, v160, v161
	v_cvt_pk_bf16_f32 v173, v162, v163
	v_pk_mul_f32 v[164:165], v[130:131], v[164:165]
	v_pk_mul_f32 v[166:167], v[132:133], v[166:167]
	v_cvt_pk_bf16_f32 v174, v164, v165
	s_nop 0
	v_cvt_pk_bf16_f32 v175, v166, v167
	global_store_dwordx2 v[168:169], v[172:173], off
	global_store_dwordx2 v[168:169], v[174:175], off offset:64
	global_store_dwordx4 v[170:171], v[160:163], off nt
	global_store_dwordx4 v[170:171], v[164:167], off offset:128 nt
	ds_read_b128 v[160:163], v176 offset:16
	s_waitcnt lgkmcnt(0)
	v_mov_b32_e32 v164, v161
	v_mov_b32_e32 v165, v162
	v_mov_b32_e32 v161, v163
	v_pk_add_f32 v[160:161], v[164:165], v[160:161]
	s_nop 0
	v_add_f32_e32 v96, v160, v161
	v_fmamk_f32 v96, v96, 0x3c000000, v251
	v_rsq_f32_e32 v96, v96
	s_nop 0
	v_pk_mul_f32 v[160:161], v[36:37], v[96:97] op_sel_hi:[1,0]
	v_pk_mul_f32 v[162:163], v[38:39], v[96:97] op_sel_hi:[1,0]
	v_pk_mul_f32 v[160:161], v[134:135], v[160:161]
	v_pk_mul_f32 v[162:163], v[136:137], v[162:163]
	v_pk_mul_f32 v[164:165], v[32:33], v[96:97] op_sel_hi:[1,0]
	v_pk_mul_f32 v[166:167], v[34:35], v[96:97] op_sel_hi:[1,0]
	v_cvt_pk_bf16_f32 v172, v160, v161
	v_cvt_pk_bf16_f32 v173, v162, v163
	v_pk_mul_f32 v[164:165], v[130:131], v[164:165]
	v_pk_mul_f32 v[166:167], v[132:133], v[166:167]
	v_cvt_pk_bf16_f32 v174, v164, v165
	s_nop 0
	v_cvt_pk_bf16_f32 v175, v166, v167
	global_store_dwordx2 v[168:169], v[172:173], off offset:256
	global_store_dwordx2 v[168:169], v[174:175], off offset:320
	global_store_dwordx4 v[170:171], v[160:163], off offset:512 nt
	global_store_dwordx4 v[170:171], v[164:167], off offset:640 nt
	v_add_u32_e32 v96, 0xa0, v182
	v_lshlrev_b32_e32 v160, 8, v96
	v_lshl_add_u32 v176, v96, 5, s4
	v_ashrrev_i32_e32 v161, 31, v160
	v_lshl_add_u64 v[168:169], v[160:161], 1, v[156:157]
	v_lshl_add_u64 v[170:171], v[160:161], 2, v[158:159]
	ds_read_b128 v[160:163], v176
	s_waitcnt lgkmcnt(0)
	v_mov_b32_e32 v164, v161
	v_mov_b32_e32 v165, v162
	v_mov_b32_e32 v161, v163
	v_pk_add_f32 v[160:161], v[164:165], v[160:161]
	s_nop 0
	v_add_f32_e32 v96, v160, v161
	v_fmamk_f32 v96, v96, 0x3c000000, v251
	v_rsq_f32_e32 v96, v96
	s_nop 0
	v_pk_mul_f32 v[160:161], v[28:29], v[96:97] op_sel_hi:[1,0]
	v_pk_mul_f32 v[162:163], v[30:31], v[96:97] op_sel_hi:[1,0]
	v_pk_mul_f32 v[160:161], v[134:135], v[160:161]
	v_pk_mul_f32 v[162:163], v[136:137], v[162:163]
	v_pk_mul_f32 v[164:165], v[24:25], v[96:97] op_sel_hi:[1,0]
	v_pk_mul_f32 v[166:167], v[26:27], v[96:97] op_sel_hi:[1,0]
	v_cvt_pk_bf16_f32 v172, v160, v161
	v_cvt_pk_bf16_f32 v173, v162, v163
	v_pk_mul_f32 v[164:165], v[130:131], v[164:165]
	v_pk_mul_f32 v[166:167], v[132:133], v[166:167]
	v_cvt_pk_bf16_f32 v174, v164, v165
	s_nop 0
	v_cvt_pk_bf16_f32 v175, v166, v167
	global_store_dwordx2 v[168:169], v[172:173], off
	global_store_dwordx2 v[168:169], v[174:175], off offset:64
	global_store_dwordx4 v[170:171], v[160:163], off nt
	global_store_dwordx4 v[170:171], v[164:167], off offset:128 nt
	ds_read_b128 v[160:163], v176 offset:16
	s_waitcnt lgkmcnt(0)
	v_mov_b32_e32 v164, v161
	v_mov_b32_e32 v165, v162
	v_mov_b32_e32 v161, v163
	v_pk_add_f32 v[160:161], v[164:165], v[160:161]
	s_nop 0
	v_add_f32_e32 v96, v160, v161
	v_fmamk_f32 v96, v96, 0x3c000000, v251
	v_rsq_f32_e32 v96, v96
	s_nop 0
	v_pk_mul_f32 v[160:161], v[20:21], v[96:97] op_sel_hi:[1,0]
	v_pk_mul_f32 v[162:163], v[22:23], v[96:97] op_sel_hi:[1,0]
	v_pk_mul_f32 v[160:161], v[134:135], v[160:161]
	v_pk_mul_f32 v[162:163], v[136:137], v[162:163]
	v_pk_mul_f32 v[164:165], v[16:17], v[96:97] op_sel_hi:[1,0]
	v_pk_mul_f32 v[166:167], v[18:19], v[96:97] op_sel_hi:[1,0]
	v_cvt_pk_bf16_f32 v172, v160, v161
	v_cvt_pk_bf16_f32 v173, v162, v163
	v_pk_mul_f32 v[164:165], v[130:131], v[164:165]
	v_pk_mul_f32 v[166:167], v[132:133], v[166:167]
	v_cvt_pk_bf16_f32 v174, v164, v165
	s_nop 0
	v_cvt_pk_bf16_f32 v175, v166, v167
	global_store_dwordx2 v[168:169], v[172:173], off offset:256
	global_store_dwordx2 v[168:169], v[174:175], off offset:320
	global_store_dwordx4 v[170:171], v[160:163], off offset:512 nt
	global_store_dwordx4 v[170:171], v[164:167], off offset:640 nt
	v_add_u32_e32 v96, 0xb0, v182
	v_lshlrev_b32_e32 v160, 8, v96
	v_lshl_add_u32 v176, v96, 5, s4
	v_ashrrev_i32_e32 v161, 31, v160
	v_lshl_add_u64 v[168:169], v[160:161], 1, v[156:157]
	v_lshl_add_u64 v[170:171], v[160:161], 2, v[158:159]
	ds_read_b128 v[160:163], v176
	s_waitcnt lgkmcnt(0)
	v_mov_b32_e32 v164, v161
	v_mov_b32_e32 v165, v162
	v_mov_b32_e32 v161, v163
	v_pk_add_f32 v[160:161], v[164:165], v[160:161]
	s_nop 0
	v_add_f32_e32 v96, v160, v161
	v_fmamk_f32 v96, v96, 0x3c000000, v251
	v_rsq_f32_e32 v96, v96
	s_nop 0
	v_pk_mul_f32 v[160:161], v[12:13], v[96:97] op_sel_hi:[1,0]
	v_pk_mul_f32 v[162:163], v[14:15], v[96:97] op_sel_hi:[1,0]
	v_pk_mul_f32 v[160:161], v[134:135], v[160:161]
	v_pk_mul_f32 v[162:163], v[136:137], v[162:163]
	v_pk_mul_f32 v[164:165], v[8:9], v[96:97] op_sel_hi:[1,0]
	v_pk_mul_f32 v[166:167], v[10:11], v[96:97] op_sel_hi:[1,0]
	v_cvt_pk_bf16_f32 v172, v160, v161
	v_cvt_pk_bf16_f32 v173, v162, v163
	v_pk_mul_f32 v[164:165], v[130:131], v[164:165]
	v_pk_mul_f32 v[166:167], v[132:133], v[166:167]
	v_cvt_pk_bf16_f32 v174, v164, v165
	s_nop 0
	v_cvt_pk_bf16_f32 v175, v166, v167
	global_store_dwordx2 v[168:169], v[172:173], off
	global_store_dwordx2 v[168:169], v[174:175], off offset:64
	global_store_dwordx4 v[170:171], v[160:163], off nt
	global_store_dwordx4 v[170:171], v[164:167], off offset:128 nt
	ds_read_b128 v[160:163], v176 offset:16
	s_waitcnt lgkmcnt(0)
	v_mov_b32_e32 v164, v161
	v_mov_b32_e32 v165, v162
	v_mov_b32_e32 v161, v163
	v_pk_add_f32 v[160:161], v[164:165], v[160:161]
	s_nop 0
	v_add_f32_e32 v96, v160, v161
	v_fmamk_f32 v96, v96, 0x3c000000, v251
	v_rsq_f32_e32 v96, v96
	s_nop 0
	v_pk_mul_f32 v[160:161], v[4:5], v[96:97] op_sel_hi:[1,0]
	v_pk_mul_f32 v[162:163], v[6:7], v[96:97] op_sel_hi:[1,0]
	v_pk_mul_f32 v[160:161], v[134:135], v[160:161]
	v_pk_mul_f32 v[162:163], v[136:137], v[162:163]
	v_pk_mul_f32 v[164:165], v[0:1], v[96:97] op_sel_hi:[1,0]
	v_pk_mul_f32 v[166:167], v[2:3], v[96:97] op_sel_hi:[1,0]
	v_cvt_pk_bf16_f32 v172, v160, v161
	v_cvt_pk_bf16_f32 v173, v162, v163
	v_pk_mul_f32 v[164:165], v[130:131], v[164:165]
	v_pk_mul_f32 v[166:167], v[132:133], v[166:167]
	v_cvt_pk_bf16_f32 v174, v164, v165
	s_nop 0
	v_cvt_pk_bf16_f32 v175, v166, v167
	global_store_dwordx2 v[168:169], v[172:173], off offset:256
	global_store_dwordx2 v[168:169], v[174:175], off offset:320
	global_store_dwordx4 v[170:171], v[160:163], off offset:512 nt
	global_store_dwordx4 v[170:171], v[164:167], off offset:640 nt
	s_mov_b64 s[4:5], 0

.LBB0_362:
	s_andn2_b64 vcc, exec, s[4:5]
	s_cbranch_vccnz .LBB0_367
	v_lshlrev_b32_e32 v176, 8, v182
	v_ashrrev_i32_e32 v177, 31, v176
	v_lshl_add_u64 v[174:175], v[176:177], 1, v[156:157]
	s_mov_b64 s[4:5], -1
	s_and_b64 vcc, exec, s[66:67]
	v_add_u32_e32 v172, 0x1000, v176
	v_add_u32_e32 v170, 0x2000, v176
	v_add_u32_e32 v168, 0x3000, v176
	v_add_u32_e32 v166, 0x8000, v176
	v_add_u32_e32 v164, 0x9000, v176
	v_add_u32_e32 v162, 0xa000, v176
	v_add_u32_e32 v160, 0xb000, v176
	s_cbranch_vccz .LBB0_365
	v_cvt_pk_bf16_f32 v184, v126, v127
	v_cvt_pk_bf16_f32 v185, v128, v129
	v_lshl_add_u64 v[176:177], v[176:177], 2, v[158:159]
	v_cvt_pk_bf16_f32 v186, v122, v123
	v_cvt_pk_bf16_f32 v187, v124, v125
	global_store_dwordx2 v[174:175], v[184:185], off
	global_store_dwordx2 v[174:175], v[186:187], off offset:64
	global_store_dwordx4 v[176:177], v[126:129], off nt
	global_store_dwordx4 v[176:177], v[122:125], off offset:128 nt
	v_cvt_pk_bf16_f32 v184, v118, v119
	v_cvt_pk_bf16_f32 v185, v120, v121
	v_cvt_pk_bf16_f32 v186, v114, v115
	v_cvt_pk_bf16_f32 v187, v116, v117
	global_store_dwordx2 v[174:175], v[184:185], off offset:256
	global_store_dwordx2 v[174:175], v[186:187], off offset:320
	global_store_dwordx4 v[176:177], v[118:121], off offset:512 nt
	global_store_dwordx4 v[176:177], v[114:117], off offset:640 nt
	v_ashrrev_i32_e32 v173, 31, v172
	v_lshl_add_u64 v[176:177], v[172:173], 1, v[156:157]
	v_cvt_pk_bf16_f32 v186, v110, v111
	v_cvt_pk_bf16_f32 v187, v112, v113
	v_lshl_add_u64 v[184:185], v[172:173], 2, v[158:159]
	v_cvt_pk_bf16_f32 v188, v106, v107
	v_cvt_pk_bf16_f32 v189, v108, v109
	global_store_dwordx2 v[176:177], v[186:187], off
	global_store_dwordx2 v[176:177], v[188:189], off offset:64
	global_store_dwordx4 v[184:185], v[110:113], off nt
	global_store_dwordx4 v[184:185], v[106:109], off offset:128 nt
	v_cvt_pk_bf16_f32 v186, v102, v103
	v_cvt_pk_bf16_f32 v187, v104, v105
	v_cvt_pk_bf16_f32 v188, v98, v99
	v_cvt_pk_bf16_f32 v189, v100, v101
	global_store_dwordx2 v[176:177], v[186:187], off offset:256
	global_store_dwordx2 v[176:177], v[188:189], off offset:320
	global_store_dwordx4 v[184:185], v[102:105], off offset:512 nt
	global_store_dwordx4 v[184:185], v[98:101], off offset:640 nt
	v_ashrrev_i32_e32 v171, 31, v170
	v_lshl_add_u64 v[176:177], v[170:171], 1, v[156:157]
	v_cvt_pk_bf16_f32 v186, v92, v93
	v_cvt_pk_bf16_f32 v187, v94, v95
	v_lshl_add_u64 v[184:185], v[170:171], 2, v[158:159]
	v_cvt_pk_bf16_f32 v188, v88, v89
	v_cvt_pk_bf16_f32 v189, v90, v91
	global_store_dwordx2 v[176:177], v[186:187], off
	global_store_dwordx2 v[176:177], v[188:189], off offset:64
	global_store_dwordx4 v[184:185], v[92:95], off nt
	global_store_dwordx4 v[184:185], v[88:91], off offset:128 nt
	v_cvt_pk_bf16_f32 v186, v84, v85
	v_cvt_pk_bf16_f32 v187, v86, v87
	v_cvt_pk_bf16_f32 v188, v80, v81
	v_cvt_pk_bf16_f32 v189, v82, v83
	global_store_dwordx2 v[176:177], v[186:187], off offset:256
	global_store_dwordx2 v[176:177], v[188:189], off offset:320
	global_store_dwordx4 v[184:185], v[84:87], off offset:512 nt
	global_store_dwordx4 v[184:185], v[80:83], off offset:640 nt
	v_ashrrev_i32_e32 v169, 31, v168
	v_lshl_add_u64 v[176:177], v[168:169], 1, v[156:157]
	v_cvt_pk_bf16_f32 v186, v76, v77
	v_cvt_pk_bf16_f32 v187, v78, v79
	v_lshl_add_u64 v[184:185], v[168:169], 2, v[158:159]
	v_cvt_pk_bf16_f32 v188, v72, v73
	v_cvt_pk_bf16_f32 v189, v74, v75
	global_store_dwordx2 v[176:177], v[186:187], off
	global_store_dwordx2 v[176:177], v[188:189], off offset:64
	global_store_dwordx4 v[184:185], v[76:79], off nt
	global_store_dwordx4 v[184:185], v[72:75], off offset:128 nt
	v_cvt_pk_bf16_f32 v186, v68, v69
	v_cvt_pk_bf16_f32 v187, v70, v71
	v_cvt_pk_bf16_f32 v188, v64, v65
	v_cvt_pk_bf16_f32 v189, v66, v67
	global_store_dwordx2 v[176:177], v[186:187], off offset:256
	global_store_dwordx2 v[176:177], v[188:189], off offset:320
	global_store_dwordx4 v[184:185], v[68:71], off offset:512 nt
	global_store_dwordx4 v[184:185], v[64:67], off offset:640 nt
	v_ashrrev_i32_e32 v167, 31, v166
	v_lshl_add_u64 v[176:177], v[166:167], 1, v[156:157]
	v_cvt_pk_bf16_f32 v186, v60, v61
	v_cvt_pk_bf16_f32 v187, v62, v63
	v_lshl_add_u64 v[184:185], v[166:167], 2, v[158:159]
	v_cvt_pk_bf16_f32 v188, v56, v57
	v_cvt_pk_bf16_f32 v189, v58, v59
	global_store_dwordx2 v[176:177], v[186:187], off
	global_store_dwordx2 v[176:177], v[188:189], off offset:64
	global_store_dwordx4 v[184:185], v[60:63], off nt
	global_store_dwordx4 v[184:185], v[56:59], off offset:128 nt
	v_cvt_pk_bf16_f32 v186, v52, v53
	v_cvt_pk_bf16_f32 v187, v54, v55
	v_cvt_pk_bf16_f32 v188, v48, v49
	v_cvt_pk_bf16_f32 v189, v50, v51
	global_store_dwordx2 v[176:177], v[186:187], off offset:256
	global_store_dwordx2 v[176:177], v[188:189], off offset:320
	global_store_dwordx4 v[184:185], v[52:55], off offset:512 nt
	global_store_dwordx4 v[184:185], v[48:51], off offset:640 nt
	v_ashrrev_i32_e32 v165, 31, v164
	v_lshl_add_u64 v[176:177], v[164:165], 1, v[156:157]
	v_cvt_pk_bf16_f32 v186, v44, v45
	v_cvt_pk_bf16_f32 v187, v46, v47
	v_lshl_add_u64 v[184:185], v[164:165], 2, v[158:159]
	v_cvt_pk_bf16_f32 v188, v40, v41
	v_cvt_pk_bf16_f32 v189, v42, v43
	global_store_dwordx2 v[176:177], v[186:187], off
	global_store_dwordx2 v[176:177], v[188:189], off offset:64
	global_store_dwordx4 v[184:185], v[44:47], off nt
	global_store_dwordx4 v[184:185], v[40:43], off offset:128 nt
	v_cvt_pk_bf16_f32 v186, v36, v37
	v_cvt_pk_bf16_f32 v187, v38, v39
	v_cvt_pk_bf16_f32 v188, v32, v33
	v_cvt_pk_bf16_f32 v189, v34, v35
	global_store_dwordx2 v[176:177], v[186:187], off offset:256
	global_store_dwordx2 v[176:177], v[188:189], off offset:320
	global_store_dwordx4 v[184:185], v[36:39], off offset:512 nt
	global_store_dwordx4 v[184:185], v[32:35], off offset:640 nt
	v_ashrrev_i32_e32 v163, 31, v162
	v_lshl_add_u64 v[176:177], v[162:163], 1, v[156:157]
	v_cvt_pk_bf16_f32 v186, v28, v29
	v_cvt_pk_bf16_f32 v187, v30, v31
	v_lshl_add_u64 v[184:185], v[162:163], 2, v[158:159]
	v_cvt_pk_bf16_f32 v188, v24, v25
	v_cvt_pk_bf16_f32 v189, v26, v27
	global_store_dwordx2 v[176:177], v[186:187], off
	global_store_dwordx2 v[176:177], v[188:189], off offset:64
	global_store_dwordx4 v[184:185], v[28:31], off nt
	global_store_dwordx4 v[184:185], v[24:27], off offset:128 nt
	v_cvt_pk_bf16_f32 v186, v20, v21
	v_cvt_pk_bf16_f32 v187, v22, v23
	v_cvt_pk_bf16_f32 v188, v16, v17
	v_cvt_pk_bf16_f32 v189, v18, v19
	global_store_dwordx2 v[176:177], v[186:187], off offset:256
	global_store_dwordx2 v[176:177], v[188:189], off offset:320
	global_store_dwordx4 v[184:185], v[20:23], off offset:512 nt
	global_store_dwordx4 v[184:185], v[16:19], off offset:640 nt
	v_ashrrev_i32_e32 v161, 31, v160
	v_lshl_add_u64 v[176:177], v[160:161], 1, v[156:157]
	v_cvt_pk_bf16_f32 v184, v12, v13
	v_cvt_pk_bf16_f32 v185, v14, v15
	v_lshl_add_u64 v[158:159], v[160:161], 2, v[158:159]
	v_cvt_pk_bf16_f32 v186, v8, v9
	v_cvt_pk_bf16_f32 v187, v10, v11
	global_store_dwordx2 v[176:177], v[184:185], off
	global_store_dwordx2 v[176:177], v[186:187], off offset:64
	global_store_dwordx4 v[158:159], v[12:15], off nt
	global_store_dwordx4 v[158:159], v[8:11], off offset:128 nt
	v_cvt_pk_bf16_f32 v184, v4, v5
	v_cvt_pk_bf16_f32 v185, v6, v7
	v_cvt_pk_bf16_f32 v186, v0, v1
	v_cvt_pk_bf16_f32 v187, v2, v3
	global_store_dwordx2 v[176:177], v[184:185], off offset:256
	global_store_dwordx2 v[176:177], v[186:187], off offset:320
	global_store_dwordx4 v[158:159], v[4:7], off offset:512 nt
	global_store_dwordx4 v[158:159], v[0:3], off offset:640 nt
	s_mov_b64 s[4:5], 0
